# P0 tconv w_in_a q|z: batch 24 tile loads (was one vmcnt(0) per load)
# speedup vs baseline: 1.0128x; 1.0106x over previous
;     ...
;     { const int c = tid & 63, r = tid >> 6; const int sc0 = cm(np * 128 + c), sc1 = cm(np * 128 + 64 + c);
;       float v0[8], v1[8];
; #pragma unroll
;       for (int pass = 0; pass < 8; ++pass) { const int k = kt * 64 + pass * 8 + r; const float g = (gk ? gk[k] : 1.f) * wsc;
;         v0[pass] = (sc0 >= 0) ? src[(size_t)k * ldS + sc0] * g : 0.f; v1[pass] = (sc1 >= 0) ? src[(size_t)k * ldS + sc1] * g : 0.f; }
; __device__ __forceinline__ void p0_prep(const Params& p, unsigned char* lds, int bid, int nb) {
;     ...
;   tconv<CmA, true>((bf16_t*)(ws + OFF_WA), 2048, p.w_in_a, 9552, 32, 128, p.norm_a, CmA{}, tl, bid, nb, 64.f);
.LBB0_63:
	s_or_b64 exec, exec, s[4:5]
	s_lshl_b32 s8, s20, 6
	v_add_u32_e32 v10, s8, v5
	v_ashrrev_i32_e32 v11, 31, v10
	v_readlane_b32 s42, v254, 2
	v_readlane_b32 s43, v254, 3
	v_readlane_b32 s44, v254, 4
	v_readlane_b32 s45, v254, 5
	v_cmp_lt_i32_e64 s[4:5], -1, v6
	v_cmp_lt_i32_e64 s[6:7], -1, v14
	s_mov_b32 s72, 0x4aa00
	s_mov_b32 s73, 0
	v_lshl_add_u64 v[40:41], v[10:11], 2, s[42:43]
	global_load_dword v42, v[40:41], off
	global_load_dword v43, v[40:41], off offset:32
	global_load_dword v44, v[40:41], off offset:64
	global_load_dword v45, v[40:41], off offset:96
	global_load_dword v46, v[40:41], off offset:128
	global_load_dword v47, v[40:41], off offset:160
	global_load_dword v48, v[40:41], off offset:192
	global_load_dword v49, v[40:41], off offset:224
	v_lshl_add_u64 v[12:13], v[6:7], 2, s[44:45]
	v_mov_b32_e32 v15, v7
	v_lshl_add_u64 v[14:15], v[14:15], 2, s[44:45]
	v_mad_i64_i32 v[12:13], s[38:39], v10, s34, v[12:13]
	v_mad_i64_i32 v[14:15], s[38:39], v10, s34, v[14:15]
	v_mov_b32_e32 v20, 0
	v_mov_b32_e32 v23, 0
	v_mov_b32_e32 v25, 0
	v_mov_b32_e32 v27, 0
	v_mov_b32_e32 v29, 0
	v_mov_b32_e32 v31, 0
	v_mov_b32_e32 v33, 0
	v_mov_b32_e32 v11, 0
	v_mov_b32_e32 v6, 0
	v_mov_b32_e32 v21, 0
	v_mov_b32_e32 v24, 0
	v_mov_b32_e32 v26, 0
	v_mov_b32_e32 v28, 0
	v_mov_b32_e32 v30, 0
	v_mov_b32_e32 v32, 0
	v_mov_b32_e32 v10, 0
	s_mov_b64 s[20:21], exec
	s_and_b64 exec, s[20:21], s[4:5]
	global_load_dword v20, v[12:13], off
	v_lshl_add_u64 v[12:13], v[12:13], 0, s[72:73]
	global_load_dword v23, v[12:13], off
	v_lshl_add_u64 v[12:13], v[12:13], 0, s[72:73]
	global_load_dword v25, v[12:13], off
	v_lshl_add_u64 v[12:13], v[12:13], 0, s[72:73]
	global_load_dword v27, v[12:13], off
	v_lshl_add_u64 v[12:13], v[12:13], 0, s[72:73]
	global_load_dword v29, v[12:13], off
	v_lshl_add_u64 v[12:13], v[12:13], 0, s[72:73]
	global_load_dword v31, v[12:13], off
	v_lshl_add_u64 v[12:13], v[12:13], 0, s[72:73]
	global_load_dword v33, v[12:13], off
	v_lshl_add_u64 v[12:13], v[12:13], 0, s[72:73]
	global_load_dword v11, v[12:13], off
	s_and_b64 exec, s[20:21], s[6:7]
	global_load_dword v6, v[14:15], off
	v_lshl_add_u64 v[14:15], v[14:15], 0, s[72:73]
	global_load_dword v21, v[14:15], off
	v_lshl_add_u64 v[14:15], v[14:15], 0, s[72:73]
	global_load_dword v24, v[14:15], off
	v_lshl_add_u64 v[14:15], v[14:15], 0, s[72:73]
	global_load_dword v26, v[14:15], off
	v_lshl_add_u64 v[14:15], v[14:15], 0, s[72:73]
	global_load_dword v28, v[14:15], off
	v_lshl_add_u64 v[14:15], v[14:15], 0, s[72:73]
	global_load_dword v30, v[14:15], off
	v_lshl_add_u64 v[14:15], v[14:15], 0, s[72:73]
	global_load_dword v32, v[14:15], off
	v_lshl_add_u64 v[14:15], v[14:15], 0, s[72:73]
	global_load_dword v10, v[14:15], off
	s_mov_b64 exec, s[20:21]
	s_waitcnt vmcnt(0)
	v_mul_f32_e32 v42, 0x42800000, v42
	v_mul_f32_e32 v43, 0x42800000, v43
	v_mul_f32_e32 v44, 0x42800000, v44
	v_mul_f32_e32 v45, 0x42800000, v45
	v_mul_f32_e32 v46, 0x42800000, v46
	v_mul_f32_e32 v47, 0x42800000, v47
	v_mul_f32_e32 v48, 0x42800000, v48
	v_mul_f32_e32 v49, 0x42800000, v49
	v_mul_f32_e32 v20, v42, v20
	v_mul_f32_e32 v6, v42, v6
	v_mul_f32_e32 v23, v43, v23
	v_mul_f32_e32 v21, v43, v21
	v_mul_f32_e32 v25, v44, v25
	v_mul_f32_e32 v24, v44, v24
	v_mul_f32_e32 v27, v45, v27
	v_mul_f32_e32 v26, v45, v26
	v_mul_f32_e32 v29, v46, v29
	v_mul_f32_e32 v28, v46, v28
	v_mul_f32_e32 v31, v47, v31
	v_mul_f32_e32 v30, v47, v30
	v_mul_f32_e32 v33, v48, v33
	v_mul_f32_e32 v32, v48, v32
	v_mul_f32_e32 v11, v49, v11
	v_mul_f32_e32 v10, v49, v10
	s_branch .LBB0_40
